# RG-LRU look-back: the publishing wave waits vmcnt(1) instead of vmcnt(0) at the slot checks (its write-through granule store may stay in flight)
# baseline (speedup 1.0000x reference)
.LBB0_334:
	s_cmp_lg_u64 s[52:53], 0
	s_cbranch_scc1 .Lrn_pub_334
	s_waitcnt vmcnt(0)
	s_branch .Lrn_pubd_334
.Lrn_pub_334:
	s_waitcnt vmcnt(1)
.Lrn_pubd_334:
	v_cmp_eq_u32_e64 s[0:1], 0, v108
	s_and_saveexec_b64 s[42:43], s[0:1]
	s_cbranch_execz .LBB0_338
	v_add_u32_e32 v108, s73, v125
	v_ashrrev_i32_e32 v109, 31, v108
	v_lshlrev_b64 v[108:109], 12, v[108:109]
	v_lshl_add_u64 v[110:111], v[102:103], 0, v[108:109]
	s_mov_b32 s0, 0
	s_mov_b64 s[68:69], 0

.Lrn_pubd_341:
	v_cmp_eq_u32_e64 s[0:1], 0, v110
	s_and_saveexec_b64 s[44:45], s[0:1]
	s_cbranch_execz .LBB0_345
	v_add_u32_e32 v110, s73, v119
	v_ashrrev_i32_e32 v111, 31, v110
	v_lshlrev_b64 v[110:111], 12, v[110:111]
	v_lshl_add_u64 v[112:113], v[102:103], 0, v[110:111]
	s_mov_b32 s0, 0
	s_mov_b64 s[70:71], 0

.Lrn_pubd_347:
	v_cmp_eq_u32_e64 s[0:1], 0, v106
	s_and_saveexec_b64 s[40:41], s[0:1]
	s_cbranch_execz .LBB0_351
	v_add_u32_e32 v106, s73, v126
	v_ashrrev_i32_e32 v107, 31, v106
	v_lshlrev_b64 v[106:107], 12, v[106:107]
	v_lshl_add_u64 v[108:109], v[102:103], 0, v[106:107]
	s_mov_b32 s0, 0
	s_mov_b64 s[44:45], 0

.Lrn_pubd_352:
	v_cmp_eq_u32_e32 vcc, 0, v104
	s_and_saveexec_b64 s[40:41], vcc
	s_cbranch_execz .LBB0_356
	v_add_u32_e32 v104, s73, v127
	v_ashrrev_i32_e32 v105, 31, v104
	v_lshlrev_b64 v[104:105], 12, v[104:105]
	v_lshl_add_u64 v[102:103], v[102:103], 0, v[104:105]
	s_mov_b32 s44, 0
	s_mov_b64 s[42:43], 0
